# SB phase: static s_setprio 1 for waves 4-7 as well (independent waves, one runs ahead)
# speedup vs baseline: 1.0005x; 1.0005x over previous
; __global__ void __launch_bounds__(NTHR, 2) mk_fwd(Args a) {
;     ...
;                         for (int rr = 0; rr < 4; ++rr) {
;                             const int bhl = rr * 8 + (li >> 2), b = 2 * xg + (bhl >> 4), h = bhl & 15; const size_t rb = (size_t)b * 2048;
;                             for (int k = 1; k >= 0; --k)
;                                 att::sb_wave_unit(QKV + rb * 3072 + h * 64, QKV + rb * 3072 + 1024 + h * 64, QKV + rb * 3072 + 2048 + h * 64, 3072, O1 + rb * 1024 + h * 64, 1024, (p * 16 + k * 8 + wave) * 32, (char*)lds + wave * 4096, lane);
;                         }
.LBB0_622:
	s_add_i32 s0, s3, -1
	s_cmp_lt_i32 s3, 2
	s_mov_b32 s3, s0
	s_setprio 0
	s_barrier
	s_cbranch_scc1 .LBB0_652
.LBB0_623:
	v_readfirstlane_b32 s0, v238
	s_nop 3
	s_cmp_ge_u32 s0, 0x100
	s_cbranch_scc0 .Lsb_prio_lo
	s_setprio 1
